# gm q2/q3 epilogue: gate loads batched (rolling 8-group prefetch in q2, 16 preloaded in q3) instead of 32 serialized load-wait round trips per tile
# baseline (speedup 1.0000x reference)
.LBB0_770:
	v_mov_b32_e32 v128, v182
	s_mov_b64 s[2:3], s[16:17]
	v_and_b32_e32 v128, 63, v128
	s_add_u32 s30, s30, s22
	v_ashrrev_i32_e32 v129, 31, v128
	s_addc_u32 s31, s31, s23
	v_lshl_add_u64 v[156:157], v[128:129], 4, s[2:3]
	v_lshl_add_u64 v[158:159], v[156:157], 0, s[4:5]
	v_lshl_add_u64 v[156:157], v[156:157], 0, s[30:31]
	s_mov_b64 s[98:99], 0x1000
	v_mov_b64_e32 v[248:249], v[158:159]
	v_mov_b64_e32 v[250:251], v[156:157]
	global_load_dwordx4 v[184:187], v[248:249], off nt
	global_load_dwordx4 v[188:191], v[250:251], off
	global_load_dwordx4 v[192:195], v[248:249], off offset:1024 nt
	global_load_dwordx4 v[196:199], v[250:251], off offset:1024
	global_load_dwordx4 v[200:203], v[248:249], off offset:2048 nt
	global_load_dwordx4 v[204:207], v[250:251], off offset:2048
	global_load_dwordx4 v[208:211], v[248:249], off offset:3072 nt
	global_load_dwordx4 v[212:215], v[250:251], off offset:3072
	v_lshl_add_u64 v[248:249], v[248:249], 0, s[98:99]
	v_lshl_add_u64 v[250:251], v[250:251], 0, s[98:99]
	global_load_dwordx4 v[216:219], v[248:249], off nt
	global_load_dwordx4 v[220:223], v[250:251], off
	global_load_dwordx4 v[224:227], v[248:249], off offset:1024 nt
	global_load_dwordx4 v[228:231], v[250:251], off offset:1024
	global_load_dwordx4 v[232:235], v[248:249], off offset:2048 nt
	global_load_dwordx4 v[236:239], v[250:251], off offset:2048
	global_load_dwordx4 v[240:243], v[248:249], off offset:3072 nt
	global_load_dwordx4 v[244:247], v[250:251], off offset:3072
	v_lshl_add_u64 v[248:249], v[248:249], 0, s[98:99]
	v_lshl_add_u64 v[250:251], v[250:251], 0, s[98:99]
	s_waitcnt vmcnt(14)
	v_mov_b64_e32 v[128:129], v[184:185]
	v_mov_b64_e32 v[130:131], v[186:187]
	v_mov_b64_e32 v[160:161], v[188:189]
	v_mov_b64_e32 v[162:163], v[190:191]
	global_load_dwordx4 v[184:187], v[248:249], off nt
	global_load_dwordx4 v[188:191], v[250:251], off
	v_lshlrev_b32_e32 v172, 16, v128
	v_lshlrev_b32_e32 v136, 16, v160
	v_and_b32_e32 v173, 0xffff0000, v128
	v_lshlrev_b32_e32 v128, 16, v161
	v_rcp_f32_e32 v170, v136
	v_and_b32_e32 v136, 0xffff0000, v160
	v_rcp_f32_e32 v160, v128
	v_and_b32_e32 v128, 0xffff0000, v161
	v_rcp_f32_e32 v161, v128
	v_lshlrev_b32_e32 v128, 16, v129
	v_and_b32_e32 v129, 0xffff0000, v129
	v_rcp_f32_e32 v171, v136
	v_pk_mul_f32 v[128:129], v[160:161], v[128:129]
	v_lshlrev_b32_e32 v160, 16, v130
	v_pk_mul_f32 v[10:11], v[10:11], v[128:129]
	v_lshlrev_b32_e32 v128, 16, v162
	v_and_b32_e32 v129, 0xffff0000, v162
	v_rcp_f32_e32 v128, v128
	v_rcp_f32_e32 v129, v129
	v_and_b32_e32 v161, 0xffff0000, v130
	v_lshlrev_b32_e32 v130, 16, v131
	v_and_b32_e32 v131, 0xffff0000, v131
	v_pk_mul_f32 v[128:129], v[128:129], v[160:161]
	v_pk_mul_f32 v[170:171], v[170:171], v[172:173]
	v_pk_mul_f32 v[12:13], v[12:13], v[128:129]
	v_lshlrev_b32_e32 v128, 16, v163
	v_and_b32_e32 v129, 0xffff0000, v163
	v_rcp_f32_e32 v128, v128
	v_rcp_f32_e32 v129, v129
	v_pk_mul_f32 v[8:9], v[8:9], v[170:171]
	v_pk_mul_f32 v[128:129], v[128:129], v[130:131]
	s_nop 0
	v_pk_mul_f32 v[14:15], v[14:15], v[128:129]
	s_waitcnt vmcnt(14)
	v_mov_b64_e32 v[128:129], v[192:193]
	v_mov_b64_e32 v[130:131], v[194:195]
	v_mov_b64_e32 v[160:161], v[196:197]
	v_mov_b64_e32 v[162:163], v[198:199]
	global_load_dwordx4 v[192:195], v[248:249], off offset:1024 nt
	global_load_dwordx4 v[196:199], v[250:251], off offset:1024
	v_lshlrev_b32_e32 v172, 16, v128
	v_lshlrev_b32_e32 v136, 16, v160
	v_and_b32_e32 v173, 0xffff0000, v128
	v_lshlrev_b32_e32 v128, 16, v161
	v_rcp_f32_e32 v170, v136
	v_and_b32_e32 v136, 0xffff0000, v160
	v_rcp_f32_e32 v160, v128
	v_and_b32_e32 v128, 0xffff0000, v161
	v_rcp_f32_e32 v161, v128
	v_lshlrev_b32_e32 v128, 16, v129
	v_and_b32_e32 v129, 0xffff0000, v129
	v_rcp_f32_e32 v171, v136
	v_pk_mul_f32 v[128:129], v[160:161], v[128:129]
	v_lshlrev_b32_e32 v160, 16, v130
	v_pk_mul_f32 v[30:31], v[30:31], v[128:129]
	v_lshlrev_b32_e32 v128, 16, v162
	v_and_b32_e32 v129, 0xffff0000, v162
	v_rcp_f32_e32 v128, v128
	v_rcp_f32_e32 v129, v129
	v_and_b32_e32 v161, 0xffff0000, v130
	v_lshlrev_b32_e32 v130, 16, v131
	v_and_b32_e32 v131, 0xffff0000, v131
	v_pk_mul_f32 v[128:129], v[128:129], v[160:161]
	v_pk_mul_f32 v[170:171], v[170:171], v[172:173]
	v_pk_mul_f32 v[32:33], v[32:33], v[128:129]
	v_lshlrev_b32_e32 v128, 16, v163
	v_and_b32_e32 v129, 0xffff0000, v163
	v_rcp_f32_e32 v128, v128
	v_rcp_f32_e32 v129, v129
	v_pk_mul_f32 v[28:29], v[28:29], v[170:171]
	v_pk_mul_f32 v[128:129], v[128:129], v[130:131]
	s_nop 0
	v_pk_mul_f32 v[34:35], v[34:35], v[128:129]
	s_nop 0
	s_waitcnt vmcnt(14)
	v_mov_b64_e32 v[128:129], v[200:201]
	v_mov_b64_e32 v[130:131], v[202:203]
	v_mov_b64_e32 v[160:161], v[204:205]
	v_mov_b64_e32 v[162:163], v[206:207]
	global_load_dwordx4 v[200:203], v[248:249], off offset:2048 nt
	global_load_dwordx4 v[204:207], v[250:251], off offset:2048
	v_lshlrev_b32_e32 v172, 16, v128
	v_lshlrev_b32_e32 v136, 16, v160
	v_and_b32_e32 v173, 0xffff0000, v128
	v_lshlrev_b32_e32 v128, 16, v161
	v_rcp_f32_e32 v170, v136
	v_and_b32_e32 v136, 0xffff0000, v160
	v_rcp_f32_e32 v160, v128
	v_and_b32_e32 v128, 0xffff0000, v161
	v_rcp_f32_e32 v161, v128
	v_lshlrev_b32_e32 v128, 16, v129
	v_and_b32_e32 v129, 0xffff0000, v129
	v_rcp_f32_e32 v171, v136
	v_pk_mul_f32 v[128:129], v[160:161], v[128:129]
	v_lshlrev_b32_e32 v160, 16, v130
	v_pk_mul_f32 v[42:43], v[42:43], v[128:129]
	v_lshlrev_b32_e32 v128, 16, v162
	v_and_b32_e32 v129, 0xffff0000, v162
	v_rcp_f32_e32 v128, v128
	v_rcp_f32_e32 v129, v129
	v_and_b32_e32 v161, 0xffff0000, v130
	v_lshlrev_b32_e32 v130, 16, v131
	v_and_b32_e32 v131, 0xffff0000, v131
	v_pk_mul_f32 v[128:129], v[128:129], v[160:161]
	v_pk_mul_f32 v[170:171], v[170:171], v[172:173]
	v_pk_mul_f32 v[44:45], v[44:45], v[128:129]
	v_lshlrev_b32_e32 v128, 16, v163
	v_and_b32_e32 v129, 0xffff0000, v163
	v_rcp_f32_e32 v128, v128
	v_rcp_f32_e32 v129, v129
	v_pk_mul_f32 v[40:41], v[40:41], v[170:171]
	v_pk_mul_f32 v[128:129], v[128:129], v[130:131]
	s_nop 0
	v_pk_mul_f32 v[46:47], v[46:47], v[128:129]
	s_waitcnt vmcnt(14)
	v_mov_b64_e32 v[128:129], v[208:209]
	v_mov_b64_e32 v[130:131], v[210:211]
	v_mov_b64_e32 v[160:161], v[212:213]
	v_mov_b64_e32 v[162:163], v[214:215]
	global_load_dwordx4 v[208:211], v[248:249], off offset:3072 nt
	global_load_dwordx4 v[212:215], v[250:251], off offset:3072
	v_lshl_add_u64 v[248:249], v[248:249], 0, s[98:99]
	v_lshl_add_u64 v[250:251], v[250:251], 0, s[98:99]
	v_lshlrev_b32_e32 v172, 16, v128
	v_lshlrev_b32_e32 v136, 16, v160
	v_and_b32_e32 v173, 0xffff0000, v128
	v_lshlrev_b32_e32 v128, 16, v161
	v_rcp_f32_e32 v170, v136
	v_and_b32_e32 v136, 0xffff0000, v160
	v_rcp_f32_e32 v160, v128
	v_and_b32_e32 v128, 0xffff0000, v161
	v_rcp_f32_e32 v161, v128
	v_lshlrev_b32_e32 v128, 16, v129
	v_and_b32_e32 v129, 0xffff0000, v129
	v_rcp_f32_e32 v171, v136
	v_pk_mul_f32 v[128:129], v[160:161], v[128:129]
	v_lshlrev_b32_e32 v160, 16, v130
	v_pk_mul_f32 v[50:51], v[50:51], v[128:129]
	v_lshlrev_b32_e32 v128, 16, v162
	v_and_b32_e32 v129, 0xffff0000, v162
	v_rcp_f32_e32 v128, v128
	v_rcp_f32_e32 v129, v129
	v_and_b32_e32 v161, 0xffff0000, v130
	v_lshlrev_b32_e32 v130, 16, v131
	v_and_b32_e32 v131, 0xffff0000, v131
	v_pk_mul_f32 v[128:129], v[128:129], v[160:161]
	v_add_co_u32_e32 v160, vcc, s82, v158
	v_pk_mul_f32 v[52:53], v[52:53], v[128:129]
	v_lshlrev_b32_e32 v128, 16, v163
	v_and_b32_e32 v129, 0xffff0000, v163
	v_rcp_f32_e32 v128, v128
	v_rcp_f32_e32 v129, v129
	v_pk_mul_f32 v[170:171], v[170:171], v[172:173]
	v_addc_co_u32_e32 v161, vcc, 0, v159, vcc
	v_pk_mul_f32 v[128:129], v[128:129], v[130:131]
	v_pk_mul_f32 v[48:49], v[48:49], v[170:171]
	v_pk_mul_f32 v[54:55], v[54:55], v[128:129]
	v_add_co_u32_e32 v162, vcc, s82, v156
	s_waitcnt vmcnt(14)
	v_mov_b64_e32 v[128:129], v[216:217]
	v_mov_b64_e32 v[130:131], v[218:219]
	s_nop 0
	v_addc_co_u32_e32 v163, vcc, 0, v157, vcc
	v_mov_b64_e32 v[170:171], v[220:221]
	v_mov_b64_e32 v[172:173], v[222:223]
	global_load_dwordx4 v[216:219], v[248:249], off nt
	global_load_dwordx4 v[220:223], v[250:251], off
	v_lshlrev_b32_e32 v176, 16, v128
	v_and_b32_e32 v177, 0xffff0000, v128
	v_lshlrev_b32_e32 v136, 16, v170
	v_lshlrev_b32_e32 v128, 16, v171
	v_rcp_f32_e32 v174, v136
	v_and_b32_e32 v136, 0xffff0000, v170
	v_rcp_f32_e32 v170, v128
	v_and_b32_e32 v128, 0xffff0000, v171
	v_rcp_f32_e32 v171, v128
	v_lshlrev_b32_e32 v128, 16, v129
	v_and_b32_e32 v129, 0xffff0000, v129
	v_rcp_f32_e32 v175, v136
	v_pk_mul_f32 v[128:129], v[170:171], v[128:129]
	v_lshlrev_b32_e32 v170, 16, v130
	v_pk_mul_f32 v[66:67], v[66:67], v[128:129]
	v_lshlrev_b32_e32 v128, 16, v172
	v_and_b32_e32 v129, 0xffff0000, v172
	v_rcp_f32_e32 v128, v128
	v_rcp_f32_e32 v129, v129
	v_and_b32_e32 v171, 0xffff0000, v130
	v_lshlrev_b32_e32 v130, 16, v131
	v_and_b32_e32 v131, 0xffff0000, v131
	v_pk_mul_f32 v[128:129], v[128:129], v[170:171]
	v_pk_mul_f32 v[174:175], v[174:175], v[176:177]
	v_pk_mul_f32 v[68:69], v[68:69], v[128:129]
	v_lshlrev_b32_e32 v128, 16, v173
	v_and_b32_e32 v129, 0xffff0000, v173
	v_rcp_f32_e32 v128, v128
	v_rcp_f32_e32 v129, v129
	v_pk_mul_f32 v[64:65], v[64:65], v[174:175]
	v_pk_mul_f32 v[128:129], v[128:129], v[130:131]
	s_nop 0
	v_pk_mul_f32 v[70:71], v[70:71], v[128:129]
	s_waitcnt vmcnt(14)
	v_mov_b64_e32 v[128:129], v[224:225]
	v_mov_b64_e32 v[130:131], v[226:227]
	v_mov_b64_e32 v[170:171], v[228:229]
	v_mov_b64_e32 v[172:173], v[230:231]
	global_load_dwordx4 v[224:227], v[248:249], off offset:1024 nt
	global_load_dwordx4 v[228:231], v[250:251], off offset:1024
	v_lshlrev_b32_e32 v176, 16, v128
	v_lshlrev_b32_e32 v136, 16, v170
	v_and_b32_e32 v177, 0xffff0000, v128
	v_lshlrev_b32_e32 v128, 16, v171
	v_rcp_f32_e32 v174, v136
	v_and_b32_e32 v136, 0xffff0000, v170
	v_rcp_f32_e32 v170, v128
	v_and_b32_e32 v128, 0xffff0000, v171
	v_rcp_f32_e32 v171, v128
	v_lshlrev_b32_e32 v128, 16, v129
	v_and_b32_e32 v129, 0xffff0000, v129
	v_rcp_f32_e32 v175, v136
	v_pk_mul_f32 v[128:129], v[170:171], v[128:129]
	v_lshlrev_b32_e32 v170, 16, v130
	v_pk_mul_f32 v[82:83], v[82:83], v[128:129]
	v_lshlrev_b32_e32 v128, 16, v172
	v_and_b32_e32 v129, 0xffff0000, v172
	v_rcp_f32_e32 v128, v128
	v_rcp_f32_e32 v129, v129
	v_and_b32_e32 v171, 0xffff0000, v130
	v_lshlrev_b32_e32 v130, 16, v131
	v_and_b32_e32 v131, 0xffff0000, v131
	v_pk_mul_f32 v[128:129], v[128:129], v[170:171]
	v_pk_mul_f32 v[174:175], v[174:175], v[176:177]
	v_pk_mul_f32 v[84:85], v[84:85], v[128:129]
	v_lshlrev_b32_e32 v128, 16, v173
	v_and_b32_e32 v129, 0xffff0000, v173
	v_rcp_f32_e32 v128, v128
	v_rcp_f32_e32 v129, v129
	v_pk_mul_f32 v[80:81], v[80:81], v[174:175]
	v_pk_mul_f32 v[128:129], v[128:129], v[130:131]
	s_nop 0
	v_pk_mul_f32 v[86:87], v[86:87], v[128:129]
	s_nop 0
	s_waitcnt vmcnt(14)
	v_mov_b64_e32 v[128:129], v[232:233]
	v_mov_b64_e32 v[130:131], v[234:235]
	v_mov_b64_e32 v[170:171], v[236:237]
	v_mov_b64_e32 v[172:173], v[238:239]
	global_load_dwordx4 v[232:235], v[248:249], off offset:2048 nt
	global_load_dwordx4 v[236:239], v[250:251], off offset:2048
	v_lshlrev_b32_e32 v176, 16, v128
	v_lshlrev_b32_e32 v136, 16, v170
	v_and_b32_e32 v177, 0xffff0000, v128
	v_lshlrev_b32_e32 v128, 16, v171
	v_rcp_f32_e32 v174, v136
	v_and_b32_e32 v136, 0xffff0000, v170
	v_rcp_f32_e32 v170, v128
	v_and_b32_e32 v128, 0xffff0000, v171
	v_rcp_f32_e32 v171, v128
	v_lshlrev_b32_e32 v128, 16, v129
	v_and_b32_e32 v129, 0xffff0000, v129
	v_rcp_f32_e32 v175, v136
	v_pk_mul_f32 v[128:129], v[170:171], v[128:129]
	v_lshlrev_b32_e32 v170, 16, v130
	v_pk_mul_f32 v[102:103], v[102:103], v[128:129]
	v_lshlrev_b32_e32 v128, 16, v172
	v_and_b32_e32 v129, 0xffff0000, v172
	v_rcp_f32_e32 v128, v128
	v_rcp_f32_e32 v129, v129
	v_and_b32_e32 v171, 0xffff0000, v130
	v_lshlrev_b32_e32 v130, 16, v131
	v_and_b32_e32 v131, 0xffff0000, v131
	v_pk_mul_f32 v[128:129], v[128:129], v[170:171]
	v_pk_mul_f32 v[174:175], v[174:175], v[176:177]
	v_pk_mul_f32 v[104:105], v[104:105], v[128:129]
	v_lshlrev_b32_e32 v128, 16, v173
	v_and_b32_e32 v129, 0xffff0000, v173
	v_rcp_f32_e32 v128, v128
	v_rcp_f32_e32 v129, v129
	v_pk_mul_f32 v[100:101], v[100:101], v[174:175]
	v_pk_mul_f32 v[128:129], v[128:129], v[130:131]
	s_nop 0
	v_pk_mul_f32 v[106:107], v[106:107], v[128:129]
	s_waitcnt vmcnt(14)
	v_mov_b64_e32 v[128:129], v[240:241]
	v_mov_b64_e32 v[130:131], v[242:243]
	s_nop 0
	v_mov_b64_e32 v[160:161], v[244:245]
	v_mov_b64_e32 v[162:163], v[246:247]
	global_load_dwordx4 v[240:243], v[248:249], off offset:3072 nt
	global_load_dwordx4 v[244:247], v[250:251], off offset:3072
	v_lshlrev_b32_e32 v172, 16, v128
	v_lshlrev_b32_e32 v136, 16, v160
	v_and_b32_e32 v173, 0xffff0000, v128
	v_lshlrev_b32_e32 v128, 16, v161
	v_rcp_f32_e32 v170, v136
	v_and_b32_e32 v136, 0xffff0000, v160
	v_rcp_f32_e32 v160, v128
	v_and_b32_e32 v128, 0xffff0000, v161
	v_rcp_f32_e32 v161, v128
	v_lshlrev_b32_e32 v128, 16, v129
	v_and_b32_e32 v129, 0xffff0000, v129
	v_rcp_f32_e32 v171, v136
	v_pk_mul_f32 v[128:129], v[160:161], v[128:129]
	v_lshlrev_b32_e32 v160, 16, v130
	v_pk_mul_f32 v[110:111], v[110:111], v[128:129]
	v_lshlrev_b32_e32 v128, 16, v162
	v_and_b32_e32 v129, 0xffff0000, v162
	v_rcp_f32_e32 v128, v128
	v_rcp_f32_e32 v129, v129
	v_and_b32_e32 v161, 0xffff0000, v130
	v_lshlrev_b32_e32 v130, 16, v131
	v_and_b32_e32 v131, 0xffff0000, v131
	v_pk_mul_f32 v[128:129], v[128:129], v[160:161]
	v_add_co_u32_e32 v160, vcc, s51, v158
	v_pk_mul_f32 v[112:113], v[112:113], v[128:129]
	v_lshlrev_b32_e32 v128, 16, v163
	v_and_b32_e32 v129, 0xffff0000, v163
	v_rcp_f32_e32 v128, v128
	v_rcp_f32_e32 v129, v129
	v_pk_mul_f32 v[170:171], v[170:171], v[172:173]
	v_addc_co_u32_e32 v161, vcc, 0, v159, vcc
	v_pk_mul_f32 v[128:129], v[128:129], v[130:131]
	v_pk_mul_f32 v[108:109], v[108:109], v[170:171]
	v_pk_mul_f32 v[114:115], v[114:115], v[128:129]
	v_add_co_u32_e32 v162, vcc, s51, v156
	s_waitcnt vmcnt(14)
	v_mov_b64_e32 v[128:129], v[184:185]
	v_mov_b64_e32 v[130:131], v[186:187]
	s_nop 0
	v_addc_co_u32_e32 v163, vcc, 0, v157, vcc
	v_mov_b64_e32 v[170:171], v[188:189]
	v_mov_b64_e32 v[172:173], v[190:191]
	v_add_co_u32_e32 v158, vcc, s83, v158
	v_lshlrev_b32_e32 v176, 16, v128
	v_and_b32_e32 v177, 0xffff0000, v128
	v_addc_co_u32_e32 v159, vcc, 0, v159, vcc
	v_lshlrev_b32_e32 v136, 16, v170
	v_lshlrev_b32_e32 v128, 16, v171
	v_rcp_f32_e32 v174, v136
	v_and_b32_e32 v136, 0xffff0000, v170
	v_rcp_f32_e32 v170, v128
	v_and_b32_e32 v128, 0xffff0000, v171
	v_rcp_f32_e32 v171, v128
	v_lshlrev_b32_e32 v128, 16, v129
	v_and_b32_e32 v129, 0xffff0000, v129
	v_rcp_f32_e32 v175, v136
	v_pk_mul_f32 v[128:129], v[170:171], v[128:129]
	v_lshlrev_b32_e32 v170, 16, v130
	v_pk_mul_f32 v[126:127], v[126:127], v[128:129]
	v_lshlrev_b32_e32 v128, 16, v172
	v_and_b32_e32 v129, 0xffff0000, v172
	v_rcp_f32_e32 v128, v128
	v_rcp_f32_e32 v129, v129
	v_and_b32_e32 v171, 0xffff0000, v130
	v_lshlrev_b32_e32 v130, 16, v131
	v_and_b32_e32 v131, 0xffff0000, v131
	v_pk_mul_f32 v[128:129], v[128:129], v[170:171]
	v_pk_mul_f32 v[174:175], v[174:175], v[176:177]
	v_pk_mul_f32 v[120:121], v[120:121], v[128:129]
	v_lshlrev_b32_e32 v128, 16, v173
	v_and_b32_e32 v129, 0xffff0000, v173
	v_rcp_f32_e32 v128, v128
	v_rcp_f32_e32 v129, v129
	v_pk_mul_f32 v[124:125], v[124:125], v[174:175]
	v_add_co_u32_e32 v156, vcc, s83, v156
	v_pk_mul_f32 v[128:129], v[128:129], v[130:131]
	s_nop 0
	v_addc_co_u32_e32 v157, vcc, 0, v157, vcc
	v_pk_mul_f32 v[122:123], v[122:123], v[128:129]
	s_waitcnt vmcnt(12)
	v_mov_b64_e32 v[128:129], v[192:193]
	v_mov_b64_e32 v[130:131], v[194:195]
	v_mov_b64_e32 v[170:171], v[196:197]
	v_mov_b64_e32 v[172:173], v[198:199]
	s_and_b64 vcc, exec, s[0:1]
	v_lshlrev_b32_e32 v176, 16, v128
	v_lshlrev_b32_e32 v136, 16, v170
	v_and_b32_e32 v177, 0xffff0000, v128
	v_lshlrev_b32_e32 v128, 16, v171
	v_rcp_f32_e32 v174, v136
	v_and_b32_e32 v136, 0xffff0000, v170
	v_rcp_f32_e32 v170, v128
	v_and_b32_e32 v128, 0xffff0000, v171
	v_rcp_f32_e32 v171, v128
	v_lshlrev_b32_e32 v128, 16, v129
	v_and_b32_e32 v129, 0xffff0000, v129
	v_rcp_f32_e32 v175, v136
	v_pk_mul_f32 v[128:129], v[170:171], v[128:129]
	v_lshlrev_b32_e32 v170, 16, v130
	v_pk_mul_f32 v[118:119], v[118:119], v[128:129]
	v_lshlrev_b32_e32 v128, 16, v172
	v_and_b32_e32 v129, 0xffff0000, v172
	v_rcp_f32_e32 v128, v128
	v_rcp_f32_e32 v129, v129
	v_and_b32_e32 v171, 0xffff0000, v130
	v_lshlrev_b32_e32 v130, 16, v131
	v_and_b32_e32 v131, 0xffff0000, v131
	v_pk_mul_f32 v[128:129], v[128:129], v[170:171]
	v_pk_mul_f32 v[174:175], v[174:175], v[176:177]
	v_pk_mul_f32 v[96:97], v[96:97], v[128:129]
	v_lshlrev_b32_e32 v128, 16, v173
	v_and_b32_e32 v129, 0xffff0000, v173
	v_rcp_f32_e32 v128, v128
	v_rcp_f32_e32 v129, v129
	v_pk_mul_f32 v[116:117], v[116:117], v[174:175]
	v_pk_mul_f32 v[128:129], v[128:129], v[130:131]
	s_nop 0
	v_pk_mul_f32 v[98:99], v[98:99], v[128:129]
	s_nop 0
	s_waitcnt vmcnt(10)
	v_mov_b64_e32 v[128:129], v[200:201]
	v_mov_b64_e32 v[130:131], v[202:203]
	v_mov_b64_e32 v[170:171], v[204:205]
	v_mov_b64_e32 v[172:173], v[206:207]
	v_lshlrev_b32_e32 v176, 16, v128
	v_lshlrev_b32_e32 v136, 16, v170
	v_and_b32_e32 v177, 0xffff0000, v128
	v_lshlrev_b32_e32 v128, 16, v171
	v_rcp_f32_e32 v174, v136
	v_and_b32_e32 v136, 0xffff0000, v170
	v_rcp_f32_e32 v170, v128
	v_and_b32_e32 v128, 0xffff0000, v171
	v_rcp_f32_e32 v171, v128
	v_lshlrev_b32_e32 v128, 16, v129
	v_and_b32_e32 v129, 0xffff0000, v129
	v_rcp_f32_e32 v175, v136
	v_pk_mul_f32 v[128:129], v[170:171], v[128:129]
	v_lshlrev_b32_e32 v170, 16, v130
	v_pk_mul_f32 v[94:95], v[94:95], v[128:129]
	v_lshlrev_b32_e32 v128, 16, v172
	v_and_b32_e32 v129, 0xffff0000, v172
	v_rcp_f32_e32 v128, v128
	v_rcp_f32_e32 v129, v129
	v_and_b32_e32 v171, 0xffff0000, v130
	v_lshlrev_b32_e32 v130, 16, v131
	v_and_b32_e32 v131, 0xffff0000, v131
	v_pk_mul_f32 v[128:129], v[128:129], v[170:171]
	v_pk_mul_f32 v[174:175], v[174:175], v[176:177]
	v_pk_mul_f32 v[88:89], v[88:89], v[128:129]
	v_lshlrev_b32_e32 v128, 16, v173
	v_and_b32_e32 v129, 0xffff0000, v173
	v_rcp_f32_e32 v128, v128
	v_rcp_f32_e32 v129, v129
	v_pk_mul_f32 v[92:93], v[92:93], v[174:175]
	v_pk_mul_f32 v[128:129], v[128:129], v[130:131]
	s_nop 0
	v_pk_mul_f32 v[90:91], v[90:91], v[128:129]
	s_waitcnt vmcnt(8)
	v_mov_b64_e32 v[128:129], v[208:209]
	v_mov_b64_e32 v[130:131], v[210:211]
	s_nop 0
	v_mov_b64_e32 v[160:161], v[212:213]
	v_mov_b64_e32 v[162:163], v[214:215]
	v_lshlrev_b32_e32 v172, 16, v128
	v_lshlrev_b32_e32 v136, 16, v160
	v_and_b32_e32 v173, 0xffff0000, v128
	v_lshlrev_b32_e32 v128, 16, v161
	v_rcp_f32_e32 v170, v136
	v_and_b32_e32 v136, 0xffff0000, v160
	v_rcp_f32_e32 v160, v128
	v_and_b32_e32 v128, 0xffff0000, v161
	v_rcp_f32_e32 v161, v128
	v_lshlrev_b32_e32 v128, 16, v129
	v_and_b32_e32 v129, 0xffff0000, v129
	v_rcp_f32_e32 v171, v136
	v_pk_mul_f32 v[128:129], v[160:161], v[128:129]
	v_lshlrev_b32_e32 v160, 16, v130
	v_pk_mul_f32 v[78:79], v[78:79], v[128:129]
	v_lshlrev_b32_e32 v128, 16, v162
	v_and_b32_e32 v129, 0xffff0000, v162
	v_rcp_f32_e32 v128, v128
	v_rcp_f32_e32 v129, v129
	v_and_b32_e32 v161, 0xffff0000, v130
	v_lshlrev_b32_e32 v130, 16, v131
	v_and_b32_e32 v131, 0xffff0000, v131
	v_pk_mul_f32 v[128:129], v[128:129], v[160:161]
	v_pk_mul_f32 v[170:171], v[170:171], v[172:173]
	v_pk_mul_f32 v[72:73], v[72:73], v[128:129]
	v_lshlrev_b32_e32 v128, 16, v163
	v_and_b32_e32 v129, 0xffff0000, v163
	v_rcp_f32_e32 v128, v128
	v_rcp_f32_e32 v129, v129
	v_pk_mul_f32 v[76:77], v[76:77], v[170:171]
	v_pk_mul_f32 v[128:129], v[128:129], v[130:131]
	s_nop 0
	v_pk_mul_f32 v[74:75], v[74:75], v[128:129]
	s_nop 0
	s_waitcnt vmcnt(6)
	v_mov_b64_e32 v[128:129], v[216:217]
	v_mov_b64_e32 v[130:131], v[218:219]
	v_mov_b64_e32 v[160:161], v[220:221]
	v_mov_b64_e32 v[162:163], v[222:223]
	v_lshlrev_b32_e32 v172, 16, v128
	v_lshlrev_b32_e32 v136, 16, v160
	v_and_b32_e32 v173, 0xffff0000, v128
	v_lshlrev_b32_e32 v128, 16, v161
	v_rcp_f32_e32 v170, v136
	v_and_b32_e32 v136, 0xffff0000, v160
	v_rcp_f32_e32 v160, v128
	v_and_b32_e32 v128, 0xffff0000, v161
	v_rcp_f32_e32 v161, v128
	v_lshlrev_b32_e32 v128, 16, v129
	v_and_b32_e32 v129, 0xffff0000, v129
	v_rcp_f32_e32 v171, v136
	v_pk_mul_f32 v[128:129], v[160:161], v[128:129]
	v_lshlrev_b32_e32 v160, 16, v130
	v_pk_mul_f32 v[62:63], v[62:63], v[128:129]
	v_lshlrev_b32_e32 v128, 16, v162
	v_and_b32_e32 v129, 0xffff0000, v162
	v_rcp_f32_e32 v128, v128
	v_rcp_f32_e32 v129, v129
	v_and_b32_e32 v161, 0xffff0000, v130
	v_lshlrev_b32_e32 v130, 16, v131
	v_and_b32_e32 v131, 0xffff0000, v131
	v_pk_mul_f32 v[128:129], v[128:129], v[160:161]
	v_pk_mul_f32 v[170:171], v[170:171], v[172:173]
	v_pk_mul_f32 v[56:57], v[56:57], v[128:129]
	v_lshlrev_b32_e32 v128, 16, v163
	v_and_b32_e32 v129, 0xffff0000, v163
	v_rcp_f32_e32 v128, v128
	v_rcp_f32_e32 v129, v129
	v_pk_mul_f32 v[60:61], v[60:61], v[170:171]
	v_pk_mul_f32 v[128:129], v[128:129], v[130:131]
	s_nop 0
	v_pk_mul_f32 v[58:59], v[58:59], v[128:129]
	s_waitcnt vmcnt(4)
	v_mov_b64_e32 v[128:129], v[224:225]
	v_mov_b64_e32 v[130:131], v[226:227]
	v_mov_b64_e32 v[160:161], v[228:229]
	v_mov_b64_e32 v[162:163], v[230:231]
	v_lshlrev_b32_e32 v172, 16, v128
	v_lshlrev_b32_e32 v136, 16, v160
	v_and_b32_e32 v173, 0xffff0000, v128
	v_lshlrev_b32_e32 v128, 16, v161
	v_rcp_f32_e32 v170, v136
	v_and_b32_e32 v136, 0xffff0000, v160
	v_rcp_f32_e32 v160, v128
	v_and_b32_e32 v128, 0xffff0000, v161
	v_rcp_f32_e32 v161, v128
	v_lshlrev_b32_e32 v128, 16, v129
	v_and_b32_e32 v129, 0xffff0000, v129
	v_rcp_f32_e32 v171, v136
	v_pk_mul_f32 v[128:129], v[160:161], v[128:129]
	v_lshlrev_b32_e32 v160, 16, v130
	v_pk_mul_f32 v[38:39], v[38:39], v[128:129]
	v_lshlrev_b32_e32 v128, 16, v162
	v_and_b32_e32 v129, 0xffff0000, v162
	v_rcp_f32_e32 v128, v128
	v_rcp_f32_e32 v129, v129
	v_and_b32_e32 v161, 0xffff0000, v130
	v_lshlrev_b32_e32 v130, 16, v131
	v_and_b32_e32 v131, 0xffff0000, v131
	v_pk_mul_f32 v[128:129], v[128:129], v[160:161]
	v_pk_mul_f32 v[170:171], v[170:171], v[172:173]
	v_pk_mul_f32 v[24:25], v[24:25], v[128:129]
	v_lshlrev_b32_e32 v128, 16, v163
	v_and_b32_e32 v129, 0xffff0000, v163
	v_rcp_f32_e32 v128, v128
	v_rcp_f32_e32 v129, v129
	v_pk_mul_f32 v[36:37], v[36:37], v[170:171]
	v_pk_mul_f32 v[128:129], v[128:129], v[130:131]
	s_nop 0
	v_pk_mul_f32 v[26:27], v[26:27], v[128:129]
	s_nop 0
	s_waitcnt vmcnt(2)
	v_mov_b64_e32 v[128:129], v[232:233]
	v_mov_b64_e32 v[130:131], v[234:235]
	v_mov_b64_e32 v[160:161], v[236:237]
	v_mov_b64_e32 v[162:163], v[238:239]
	v_lshlrev_b32_e32 v172, 16, v128
	v_lshlrev_b32_e32 v136, 16, v160
	v_and_b32_e32 v173, 0xffff0000, v128
	v_lshlrev_b32_e32 v128, 16, v161
	v_rcp_f32_e32 v170, v136
	v_and_b32_e32 v136, 0xffff0000, v160
	v_rcp_f32_e32 v160, v128
	v_and_b32_e32 v128, 0xffff0000, v161
	v_rcp_f32_e32 v161, v128
	v_lshlrev_b32_e32 v128, 16, v129
	v_and_b32_e32 v129, 0xffff0000, v129
	v_rcp_f32_e32 v171, v136
	v_pk_mul_f32 v[128:129], v[160:161], v[128:129]
	v_lshlrev_b32_e32 v160, 16, v130
	v_pk_mul_f32 v[22:23], v[22:23], v[128:129]
	v_lshlrev_b32_e32 v128, 16, v162
	v_and_b32_e32 v129, 0xffff0000, v162
	v_rcp_f32_e32 v128, v128
	v_rcp_f32_e32 v129, v129
	v_and_b32_e32 v161, 0xffff0000, v130
	v_lshlrev_b32_e32 v130, 16, v131
	v_and_b32_e32 v131, 0xffff0000, v131
	v_pk_mul_f32 v[128:129], v[128:129], v[160:161]
	v_pk_mul_f32 v[170:171], v[170:171], v[172:173]
	v_pk_mul_f32 v[16:17], v[16:17], v[128:129]
	v_lshlrev_b32_e32 v128, 16, v163
	v_and_b32_e32 v129, 0xffff0000, v163
	v_rcp_f32_e32 v128, v128
	v_rcp_f32_e32 v129, v129
	v_pk_mul_f32 v[20:21], v[20:21], v[170:171]
	v_pk_mul_f32 v[128:129], v[128:129], v[130:131]
	s_nop 0
	v_pk_mul_f32 v[18:19], v[18:19], v[128:129]
	s_waitcnt vmcnt(0)
	v_mov_b64_e32 v[128:129], v[240:241]
	v_mov_b64_e32 v[130:131], v[242:243]
	s_nop 0
	v_mov_b64_e32 v[156:157], v[244:245]
	v_mov_b64_e32 v[158:159], v[246:247]
	v_lshlrev_b32_e32 v162, 16, v128
	v_lshlrev_b32_e32 v136, 16, v156
	v_and_b32_e32 v163, 0xffff0000, v128
	v_lshlrev_b32_e32 v128, 16, v157
	v_rcp_f32_e32 v160, v136
	v_and_b32_e32 v136, 0xffff0000, v156
	v_rcp_f32_e32 v156, v128
	v_and_b32_e32 v128, 0xffff0000, v157
	v_rcp_f32_e32 v157, v128
	v_lshlrev_b32_e32 v128, 16, v129
	v_and_b32_e32 v129, 0xffff0000, v129
	v_rcp_f32_e32 v161, v136
	v_pk_mul_f32 v[128:129], v[156:157], v[128:129]
	v_lshlrev_b32_e32 v156, 16, v130
	v_pk_mul_f32 v[6:7], v[6:7], v[128:129]
	v_lshlrev_b32_e32 v128, 16, v158
	v_and_b32_e32 v129, 0xffff0000, v158
	v_rcp_f32_e32 v128, v128
	v_rcp_f32_e32 v129, v129
	v_and_b32_e32 v157, 0xffff0000, v130
	v_lshlrev_b32_e32 v130, 16, v131
	v_and_b32_e32 v131, 0xffff0000, v131
	v_pk_mul_f32 v[128:129], v[128:129], v[156:157]
	v_pk_mul_f32 v[160:161], v[160:161], v[162:163]
	v_pk_mul_f32 v[0:1], v[0:1], v[128:129]
	v_lshlrev_b32_e32 v128, 16, v159
	v_and_b32_e32 v129, 0xffff0000, v159
	v_rcp_f32_e32 v128, v128
	v_rcp_f32_e32 v129, v129
	v_pk_mul_f32 v[4:5], v[4:5], v[160:161]
	v_pk_mul_f32 v[128:129], v[128:129], v[130:131]
	s_nop 0
	v_pk_mul_f32 v[2:3], v[2:3], v[128:129]
	s_nop 0
	s_cbranch_vccnz .LBB0_772
	s_barrier

.LBB0_776:
	v_mov_b32_e32 v128, v182
	s_mov_b64 s[10:11], s[16:17]
	v_and_b32_e32 v128, 63, v128
	v_readlane_b32 s96, v252, 26
	v_ashrrev_i32_e32 v129, 31, v128
	v_lshl_add_u64 v[130:131], v[128:129], 4, s[10:11]
	v_lshl_add_u64 v[130:131], v[130:131], 0, s[30:31]
	s_mov_b64 s[98:99], 0x1000
	v_mov_b64_e32 v[248:249], v[130:131]
	global_load_dwordx4 v[184:187], v[248:249], off nt
	global_load_dwordx4 v[188:191], v[248:249], off offset:1024 nt
	global_load_dwordx4 v[192:195], v[248:249], off offset:2048 nt
	global_load_dwordx4 v[196:199], v[248:249], off offset:3072 nt
	v_lshl_add_u64 v[248:249], v[248:249], 0, s[98:99]
	global_load_dwordx4 v[200:203], v[248:249], off nt
	global_load_dwordx4 v[204:207], v[248:249], off offset:1024 nt
	global_load_dwordx4 v[208:211], v[248:249], off offset:2048 nt
	global_load_dwordx4 v[212:215], v[248:249], off offset:3072 nt
	v_lshl_add_u64 v[248:249], v[248:249], 0, s[98:99]
	global_load_dwordx4 v[216:219], v[248:249], off nt
	global_load_dwordx4 v[220:223], v[248:249], off offset:1024 nt
	global_load_dwordx4 v[224:227], v[248:249], off offset:2048 nt
	global_load_dwordx4 v[228:231], v[248:249], off offset:3072 nt
	v_lshl_add_u64 v[248:249], v[248:249], 0, s[98:99]
	global_load_dwordx4 v[232:235], v[248:249], off nt
	global_load_dwordx4 v[236:239], v[248:249], off offset:1024 nt
	global_load_dwordx4 v[240:243], v[248:249], off offset:2048 nt
	global_load_dwordx4 v[244:247], v[248:249], off offset:3072 nt
	s_waitcnt vmcnt(15)
	s_nop 1
	v_mov_b64_e32 v[160:161], v[184:185]
	v_mov_b64_e32 v[162:163], v[186:187]
	s_lshl_b32 s10, s12, 8
	s_add_i32 s10, s10, s52
	v_and_or_b32 v158, v128, 15, s10
	v_ashrrev_i32_e32 v128, 1, v128
	v_and_b32_e32 v128, -8, v128
	v_ashrrev_i32_e32 v159, 31, v158
	s_lshl_b32 s12, s24, 8
	v_add_u32_e32 v128, s53, v128
	v_lshlrev_b64 v[156:157], 12, v[158:159]
	s_lshl_b64 s[24:25], s[12:13], 1
	v_lshl_add_u64 v[156:157], s[8:9], 0, v[156:157]
	v_ashrrev_i32_e32 v129, 31, v128
	v_lshl_add_u64 v[168:169], v[156:157], 0, s[24:25]
	v_lshlrev_b64 v[156:157], 1, v[128:129]
	v_lshl_add_u64 v[128:129], v[168:169], 0, v[156:157]
	s_mov_b32 s10, 0x80000
	v_lshlrev_b32_e32 v168, 16, v160
	v_and_b32_e32 v169, 0xffff0000, v160
	v_lshlrev_b32_e32 v160, 16, v161
	v_and_b32_e32 v161, 0xffff0000, v161
	v_lshlrev_b32_e32 v170, 16, v162
	v_and_b32_e32 v171, 0xffff0000, v162
	v_lshlrev_b32_e32 v162, 16, v163
	v_and_b32_e32 v163, 0xffff0000, v163
	v_pk_mul_f32 v[8:9], v[8:9], v[168:169]
	v_pk_mul_f32 v[10:11], v[10:11], v[160:161]
	v_pk_mul_f32 v[12:13], v[12:13], v[170:171]
	v_pk_mul_f32 v[14:15], v[14:15], v[162:163]
	v_cvt_pk_bf16_f32 v8, v8, v9
	v_cvt_pk_bf16_f32 v9, v10, v11
	v_cvt_pk_bf16_f32 v10, v12, v13
	v_cvt_pk_bf16_f32 v11, v14, v15
	global_store_dwordx4 v[128:129], v[8:11], off
	s_waitcnt vmcnt(15)
	s_nop 1
	v_mov_b64_e32 v[8:9], v[188:189]
	v_mov_b64_e32 v[10:11], v[190:191]
	v_lshlrev_b32_e32 v12, 16, v8
	v_and_b32_e32 v13, 0xffff0000, v8
	v_lshlrev_b32_e32 v8, 16, v9
	v_and_b32_e32 v9, 0xffff0000, v9
	v_lshlrev_b32_e32 v14, 16, v10
	v_and_b32_e32 v15, 0xffff0000, v10
	v_lshlrev_b32_e32 v10, 16, v11
	v_and_b32_e32 v11, 0xffff0000, v11
	v_pk_mul_f32 v[12:13], v[28:29], v[12:13]
	v_pk_mul_f32 v[28:29], v[30:31], v[8:9]
	v_pk_mul_f32 v[14:15], v[32:33], v[14:15]
	v_pk_mul_f32 v[30:31], v[34:35], v[10:11]
	v_cvt_pk_bf16_f32 v8, v12, v13
	v_cvt_pk_bf16_f32 v9, v28, v29
	v_cvt_pk_bf16_f32 v10, v14, v15
	v_cvt_pk_bf16_f32 v11, v30, v31
	global_store_dwordx4 v[128:129], v[8:11], off offset:256
	s_waitcnt vmcnt(15)
	s_nop 1
	v_mov_b64_e32 v[8:9], v[192:193]
	v_mov_b64_e32 v[10:11], v[194:195]
	v_or_b32_e32 v12, 16, v158
	v_ashrrev_i32_e32 v13, 31, v12
	v_lshlrev_b64 v[12:13], 12, v[12:13]
	v_lshl_add_u64 v[12:13], s[8:9], 0, v[12:13]
	v_lshl_add_u64 v[12:13], v[12:13], 0, s[24:25]
	v_lshl_add_u64 v[12:13], v[12:13], 0, v[156:157]
	v_lshlrev_b32_e32 v14, 16, v8
	v_and_b32_e32 v15, 0xffff0000, v8
	v_lshlrev_b32_e32 v8, 16, v9
	v_and_b32_e32 v9, 0xffff0000, v9
	v_lshlrev_b32_e32 v28, 16, v10
	v_and_b32_e32 v29, 0xffff0000, v10
	v_lshlrev_b32_e32 v10, 16, v11
	v_and_b32_e32 v11, 0xffff0000, v11
	v_pk_mul_f32 v[14:15], v[40:41], v[14:15]
	v_pk_mul_f32 v[30:31], v[42:43], v[8:9]
	v_pk_mul_f32 v[28:29], v[44:45], v[28:29]
	v_pk_mul_f32 v[32:33], v[46:47], v[10:11]
	v_cvt_pk_bf16_f32 v8, v14, v15
	v_cvt_pk_bf16_f32 v9, v30, v31
	v_cvt_pk_bf16_f32 v10, v28, v29
	v_cvt_pk_bf16_f32 v11, v32, v33
	global_store_dwordx4 v[12:13], v[8:11], off
	s_waitcnt vmcnt(15)
	s_nop 1
	v_mov_b64_e32 v[8:9], v[196:197]
	v_mov_b64_e32 v[10:11], v[198:199]
	v_add_co_u32_e32 v14, vcc, s82, v130
	v_lshlrev_b32_e32 v28, 16, v8
	v_and_b32_e32 v29, 0xffff0000, v8
	v_lshlrev_b32_e32 v8, 16, v9
	v_and_b32_e32 v9, 0xffff0000, v9
	v_lshlrev_b32_e32 v30, 16, v10
	v_and_b32_e32 v31, 0xffff0000, v10
	v_lshlrev_b32_e32 v10, 16, v11
	v_and_b32_e32 v11, 0xffff0000, v11
	v_pk_mul_f32 v[28:29], v[48:49], v[28:29]
	v_pk_mul_f32 v[32:33], v[50:51], v[8:9]
	v_pk_mul_f32 v[30:31], v[52:53], v[30:31]
	v_pk_mul_f32 v[34:35], v[54:55], v[10:11]
	v_cvt_pk_bf16_f32 v8, v28, v29
	v_cvt_pk_bf16_f32 v9, v32, v33
	v_cvt_pk_bf16_f32 v10, v30, v31
	v_cvt_pk_bf16_f32 v11, v34, v35
	global_store_dwordx4 v[12:13], v[8:11], off offset:256
	v_addc_co_u32_e32 v15, vcc, 0, v131, vcc
	s_waitcnt vmcnt(15)
	s_nop 1
	v_mov_b64_e32 v[8:9], v[200:201]
	v_mov_b64_e32 v[10:11], v[202:203]
	v_or_b32_e32 v12, 32, v158
	v_ashrrev_i32_e32 v13, 31, v12
	v_lshlrev_b64 v[12:13], 12, v[12:13]
	v_lshl_add_u64 v[12:13], s[8:9], 0, v[12:13]
	v_lshl_add_u64 v[12:13], v[12:13], 0, s[24:25]
	v_lshl_add_u64 v[12:13], v[12:13], 0, v[156:157]
	v_lshlrev_b32_e32 v28, 16, v8
	v_and_b32_e32 v29, 0xffff0000, v8
	v_lshlrev_b32_e32 v8, 16, v9
	v_and_b32_e32 v9, 0xffff0000, v9
	v_lshlrev_b32_e32 v30, 16, v10
	v_and_b32_e32 v31, 0xffff0000, v10
	v_lshlrev_b32_e32 v10, 16, v11
	v_and_b32_e32 v11, 0xffff0000, v11
	v_pk_mul_f32 v[28:29], v[64:65], v[28:29]
	v_pk_mul_f32 v[32:33], v[66:67], v[8:9]
	v_pk_mul_f32 v[30:31], v[68:69], v[30:31]
	v_pk_mul_f32 v[34:35], v[70:71], v[10:11]
	v_cvt_pk_bf16_f32 v8, v28, v29
	v_cvt_pk_bf16_f32 v9, v32, v33
	v_cvt_pk_bf16_f32 v10, v30, v31
	v_cvt_pk_bf16_f32 v11, v34, v35
	global_store_dwordx4 v[12:13], v[8:11], off
	s_waitcnt vmcnt(15)
	s_nop 1
	v_mov_b64_e32 v[8:9], v[204:205]
	v_mov_b64_e32 v[10:11], v[206:207]
	v_lshlrev_b32_e32 v28, 16, v8
	v_and_b32_e32 v29, 0xffff0000, v8
	v_lshlrev_b32_e32 v8, 16, v9
	v_and_b32_e32 v9, 0xffff0000, v9
	v_lshlrev_b32_e32 v30, 16, v10
	v_and_b32_e32 v31, 0xffff0000, v10
	v_lshlrev_b32_e32 v10, 16, v11
	v_and_b32_e32 v11, 0xffff0000, v11
	v_pk_mul_f32 v[28:29], v[80:81], v[28:29]
	v_pk_mul_f32 v[32:33], v[82:83], v[8:9]
	v_pk_mul_f32 v[30:31], v[84:85], v[30:31]
	v_pk_mul_f32 v[34:35], v[86:87], v[10:11]
	v_cvt_pk_bf16_f32 v8, v28, v29
	v_cvt_pk_bf16_f32 v9, v32, v33
	v_cvt_pk_bf16_f32 v10, v30, v31
	v_cvt_pk_bf16_f32 v11, v34, v35
	global_store_dwordx4 v[12:13], v[8:11], off offset:256
	s_waitcnt vmcnt(15)
	s_nop 1
	v_mov_b64_e32 v[8:9], v[208:209]
	v_mov_b64_e32 v[10:11], v[210:211]
	v_or_b32_e32 v12, 48, v158
	v_ashrrev_i32_e32 v13, 31, v12
	v_lshlrev_b64 v[12:13], 12, v[12:13]
	v_lshl_add_u64 v[12:13], s[8:9], 0, v[12:13]
	v_lshl_add_u64 v[12:13], v[12:13], 0, s[24:25]
	v_lshl_add_u64 v[12:13], v[12:13], 0, v[156:157]
	v_lshlrev_b32_e32 v28, 16, v8
	v_and_b32_e32 v29, 0xffff0000, v8
	v_lshlrev_b32_e32 v8, 16, v9
	v_and_b32_e32 v9, 0xffff0000, v9
	v_lshlrev_b32_e32 v30, 16, v10
	v_and_b32_e32 v31, 0xffff0000, v10
	v_lshlrev_b32_e32 v10, 16, v11
	v_and_b32_e32 v11, 0xffff0000, v11
	v_pk_mul_f32 v[28:29], v[100:101], v[28:29]
	v_pk_mul_f32 v[32:33], v[102:103], v[8:9]
	v_pk_mul_f32 v[30:31], v[104:105], v[30:31]
	v_pk_mul_f32 v[34:35], v[106:107], v[10:11]
	v_cvt_pk_bf16_f32 v8, v28, v29
	v_cvt_pk_bf16_f32 v9, v32, v33
	v_cvt_pk_bf16_f32 v10, v30, v31
	v_cvt_pk_bf16_f32 v11, v34, v35
	global_store_dwordx4 v[12:13], v[8:11], off
	s_waitcnt vmcnt(15)
	s_nop 1
	v_mov_b64_e32 v[8:9], v[212:213]
	v_mov_b64_e32 v[10:11], v[214:215]
	v_add_co_u32_e32 v14, vcc, s51, v130
	v_lshlrev_b32_e32 v28, 16, v8
	v_and_b32_e32 v29, 0xffff0000, v8
	v_lshlrev_b32_e32 v8, 16, v9
	v_and_b32_e32 v9, 0xffff0000, v9
	v_lshlrev_b32_e32 v30, 16, v10
	v_and_b32_e32 v31, 0xffff0000, v10
	v_lshlrev_b32_e32 v10, 16, v11
	v_and_b32_e32 v11, 0xffff0000, v11
	v_pk_mul_f32 v[28:29], v[108:109], v[28:29]
	v_pk_mul_f32 v[32:33], v[110:111], v[8:9]
	v_pk_mul_f32 v[30:31], v[112:113], v[30:31]
	v_pk_mul_f32 v[34:35], v[114:115], v[10:11]
	v_cvt_pk_bf16_f32 v8, v28, v29
	v_cvt_pk_bf16_f32 v9, v32, v33
	v_cvt_pk_bf16_f32 v10, v30, v31
	v_cvt_pk_bf16_f32 v11, v34, v35
	global_store_dwordx4 v[12:13], v[8:11], off offset:256
	v_addc_co_u32_e32 v15, vcc, 0, v131, vcc
	s_waitcnt vmcnt(15)
	s_nop 1
	v_mov_b64_e32 v[8:9], v[216:217]
	v_mov_b64_e32 v[10:11], v[218:219]
	v_add_co_u32_e32 v12, vcc, s10, v128
	s_mov_b64 s[10:11], 0x80000
	s_nop 0
	v_addc_co_u32_e32 v13, vcc, 0, v129, vcc
	v_lshlrev_b32_e32 v28, 16, v8
	v_and_b32_e32 v29, 0xffff0000, v8
	v_lshlrev_b32_e32 v8, 16, v9
	v_and_b32_e32 v9, 0xffff0000, v9
	v_lshlrev_b32_e32 v30, 16, v10
	v_and_b32_e32 v31, 0xffff0000, v10
	v_lshlrev_b32_e32 v10, 16, v11
	v_and_b32_e32 v11, 0xffff0000, v11
	v_pk_mul_f32 v[28:29], v[124:125], v[28:29]
	v_pk_mul_f32 v[32:33], v[126:127], v[8:9]
	v_pk_mul_f32 v[30:31], v[120:121], v[30:31]
	v_pk_mul_f32 v[34:35], v[122:123], v[10:11]
	v_cvt_pk_bf16_f32 v8, v28, v29
	v_cvt_pk_bf16_f32 v9, v32, v33
	v_cvt_pk_bf16_f32 v10, v30, v31
	v_cvt_pk_bf16_f32 v11, v34, v35
	global_store_dwordx4 v[12:13], v[8:11], off
	s_waitcnt vmcnt(15)
	s_nop 1
	v_mov_b64_e32 v[8:9], v[220:221]
	v_mov_b64_e32 v[10:11], v[222:223]
	v_lshl_add_u64 v[12:13], v[128:129], 0, s[10:11]
	s_mov_b32 s10, 0x90000
	v_lshlrev_b32_e32 v28, 16, v8
	v_and_b32_e32 v29, 0xffff0000, v8
	v_lshlrev_b32_e32 v8, 16, v9
	v_and_b32_e32 v9, 0xffff0000, v9
	v_lshlrev_b32_e32 v30, 16, v10
	v_and_b32_e32 v31, 0xffff0000, v10
	v_lshlrev_b32_e32 v10, 16, v11
	v_and_b32_e32 v11, 0xffff0000, v11
	v_pk_mul_f32 v[28:29], v[116:117], v[28:29]
	v_pk_mul_f32 v[32:33], v[118:119], v[8:9]
	v_pk_mul_f32 v[30:31], v[96:97], v[30:31]
	v_pk_mul_f32 v[34:35], v[98:99], v[10:11]
	v_cvt_pk_bf16_f32 v8, v28, v29
	v_cvt_pk_bf16_f32 v9, v32, v33
	v_cvt_pk_bf16_f32 v10, v30, v31
	v_cvt_pk_bf16_f32 v11, v34, v35
	global_store_dwordx4 v[12:13], v[8:11], off offset:256
	s_waitcnt vmcnt(15)
	s_nop 1
	v_mov_b64_e32 v[8:9], v[224:225]
	v_mov_b64_e32 v[10:11], v[226:227]
	v_add_co_u32_e32 v12, vcc, s10, v128
	s_mov_b64 s[10:11], 0x90000
	s_nop 0
	v_addc_co_u32_e32 v13, vcc, 0, v129, vcc
	v_lshlrev_b32_e32 v28, 16, v8
	v_and_b32_e32 v29, 0xffff0000, v8
	v_lshlrev_b32_e32 v8, 16, v9
	v_and_b32_e32 v9, 0xffff0000, v9
	v_lshlrev_b32_e32 v30, 16, v10
	v_and_b32_e32 v31, 0xffff0000, v10
	v_lshlrev_b32_e32 v10, 16, v11
	v_and_b32_e32 v11, 0xffff0000, v11
	v_pk_mul_f32 v[28:29], v[92:93], v[28:29]
	v_pk_mul_f32 v[32:33], v[94:95], v[8:9]
	v_pk_mul_f32 v[30:31], v[88:89], v[30:31]
	v_pk_mul_f32 v[34:35], v[90:91], v[10:11]
	v_cvt_pk_bf16_f32 v8, v28, v29
	v_cvt_pk_bf16_f32 v9, v32, v33
	v_cvt_pk_bf16_f32 v10, v30, v31
	v_cvt_pk_bf16_f32 v11, v34, v35
	global_store_dwordx4 v[12:13], v[8:11], off
	s_waitcnt vmcnt(15)
	s_nop 1
	v_mov_b64_e32 v[8:9], v[228:229]
	v_mov_b64_e32 v[10:11], v[230:231]
	v_lshl_add_u64 v[14:15], v[128:129], 0, s[10:11]
	v_add_co_u32_e32 v12, vcc, s83, v130
	s_mov_b32 s10, 0xa0000
	s_nop 0
	v_addc_co_u32_e32 v13, vcc, 0, v131, vcc
	v_lshlrev_b32_e32 v28, 16, v8
	v_and_b32_e32 v29, 0xffff0000, v8
	v_lshlrev_b32_e32 v8, 16, v9
	v_and_b32_e32 v9, 0xffff0000, v9
	v_lshlrev_b32_e32 v30, 16, v10
	v_and_b32_e32 v31, 0xffff0000, v10
	v_lshlrev_b32_e32 v10, 16, v11
	v_and_b32_e32 v11, 0xffff0000, v11
	v_pk_mul_f32 v[28:29], v[76:77], v[28:29]
	v_pk_mul_f32 v[32:33], v[78:79], v[8:9]
	v_pk_mul_f32 v[30:31], v[72:73], v[30:31]
	v_pk_mul_f32 v[34:35], v[74:75], v[10:11]
	v_cvt_pk_bf16_f32 v8, v28, v29
	v_cvt_pk_bf16_f32 v9, v32, v33
	v_cvt_pk_bf16_f32 v10, v30, v31
	v_cvt_pk_bf16_f32 v11, v34, v35
	global_store_dwordx4 v[14:15], v[8:11], off offset:256
	s_waitcnt vmcnt(15)
	s_nop 1
	v_mov_b64_e32 v[8:9], v[232:233]
	v_mov_b64_e32 v[10:11], v[234:235]
	v_add_co_u32_e32 v14, vcc, s10, v128
	s_mov_b64 s[10:11], 0xa0000
	s_nop 0
	v_addc_co_u32_e32 v15, vcc, 0, v129, vcc
	v_lshlrev_b32_e32 v28, 16, v8
	v_and_b32_e32 v29, 0xffff0000, v8
	v_lshlrev_b32_e32 v8, 16, v9
	v_and_b32_e32 v9, 0xffff0000, v9
	v_lshlrev_b32_e32 v30, 16, v10
	v_and_b32_e32 v31, 0xffff0000, v10
	v_lshlrev_b32_e32 v10, 16, v11
	v_and_b32_e32 v11, 0xffff0000, v11
	v_pk_mul_f32 v[28:29], v[60:61], v[28:29]
	v_pk_mul_f32 v[32:33], v[62:63], v[8:9]
	v_pk_mul_f32 v[30:31], v[56:57], v[30:31]
	v_pk_mul_f32 v[34:35], v[58:59], v[10:11]
	v_cvt_pk_bf16_f32 v8, v28, v29
	v_cvt_pk_bf16_f32 v9, v32, v33
	v_cvt_pk_bf16_f32 v10, v30, v31
	v_cvt_pk_bf16_f32 v11, v34, v35
	global_store_dwordx4 v[14:15], v[8:11], off
	s_waitcnt vmcnt(15)
	s_nop 1
	v_mov_b64_e32 v[8:9], v[236:237]
	v_mov_b64_e32 v[10:11], v[238:239]
	v_lshl_add_u64 v[14:15], v[128:129], 0, s[10:11]
	s_mov_b32 s10, 0xb0000
	v_lshlrev_b32_e32 v28, 16, v8
	v_and_b32_e32 v29, 0xffff0000, v8
	v_lshlrev_b32_e32 v8, 16, v9
	v_and_b32_e32 v9, 0xffff0000, v9
	v_lshlrev_b32_e32 v30, 16, v10
	v_and_b32_e32 v31, 0xffff0000, v10
	v_lshlrev_b32_e32 v10, 16, v11
	v_and_b32_e32 v11, 0xffff0000, v11
	v_pk_mul_f32 v[28:29], v[36:37], v[28:29]
	v_pk_mul_f32 v[32:33], v[38:39], v[8:9]
	v_pk_mul_f32 v[24:25], v[24:25], v[30:31]
	v_pk_mul_f32 v[26:27], v[26:27], v[10:11]
	v_cvt_pk_bf16_f32 v8, v28, v29
	v_cvt_pk_bf16_f32 v9, v32, v33
	v_cvt_pk_bf16_f32 v10, v24, v25
	v_cvt_pk_bf16_f32 v11, v26, v27
	global_store_dwordx4 v[14:15], v[8:11], off offset:256
	s_waitcnt vmcnt(15)
	s_nop 1
	v_mov_b64_e32 v[8:9], v[240:241]
	v_mov_b64_e32 v[10:11], v[242:243]
	v_add_co_u32_e32 v14, vcc, s10, v128
	s_mov_b64 s[10:11], 0xb0000
	s_nop 0
	v_addc_co_u32_e32 v15, vcc, 0, v129, vcc
	s_andn2_b64 vcc, exec, s[4:5]
	s_mov_b64 s[4:5], -1
	v_lshlrev_b32_e32 v24, 16, v8
	v_and_b32_e32 v25, 0xffff0000, v8
	v_lshlrev_b32_e32 v8, 16, v9
	v_and_b32_e32 v9, 0xffff0000, v9
	v_lshlrev_b32_e32 v26, 16, v10
	v_and_b32_e32 v27, 0xffff0000, v10
	v_lshlrev_b32_e32 v10, 16, v11
	v_and_b32_e32 v11, 0xffff0000, v11
	v_pk_mul_f32 v[20:21], v[20:21], v[24:25]
	v_pk_mul_f32 v[22:23], v[22:23], v[8:9]
	v_pk_mul_f32 v[16:17], v[16:17], v[26:27]
	v_pk_mul_f32 v[18:19], v[18:19], v[10:11]
	v_cvt_pk_bf16_f32 v8, v20, v21
	v_cvt_pk_bf16_f32 v9, v22, v23
	v_cvt_pk_bf16_f32 v10, v16, v17
	v_cvt_pk_bf16_f32 v11, v18, v19
	global_store_dwordx4 v[14:15], v[8:11], off
	s_waitcnt vmcnt(15)
	s_nop 1
	v_mov_b64_e32 v[8:9], v[244:245]
	v_mov_b64_e32 v[10:11], v[246:247]
	v_lshl_add_u64 v[12:13], v[128:129], 0, s[10:11]
	v_lshlrev_b32_e32 v14, 16, v8
	v_and_b32_e32 v15, 0xffff0000, v8
	v_lshlrev_b32_e32 v8, 16, v9
	v_and_b32_e32 v9, 0xffff0000, v9
	v_lshlrev_b32_e32 v16, 16, v10
	v_and_b32_e32 v17, 0xffff0000, v10
	v_lshlrev_b32_e32 v10, 16, v11
	v_and_b32_e32 v11, 0xffff0000, v11
	v_pk_mul_f32 v[4:5], v[4:5], v[14:15]
	v_pk_mul_f32 v[6:7], v[6:7], v[8:9]
	v_pk_mul_f32 v[8:9], v[0:1], v[16:17]
	v_pk_mul_f32 v[10:11], v[2:3], v[10:11]
	v_cvt_pk_bf16_f32 v0, v4, v5
	v_cvt_pk_bf16_f32 v1, v6, v7
	v_cvt_pk_bf16_f32 v2, v8, v9
	v_cvt_pk_bf16_f32 v3, v10, v11
	global_store_dwordx4 v[12:13], v[0:3], off offset:256
	s_cbranch_vccnz .LBB0_753
	s_and_b64 vcc, exec, s[0:1]
	s_cbranch_vccnz .LBB0_752
	s_barrier
	s_branch .LBB0_752
